# cooperative-groups grid sync replaced by flag wait + XCD barrier; P4 S5a U loads merged
# speedup vs baseline: 1.0508x; 1.0183x over previous
.LBB0_4:
	v_add_u32_e32 v1, 0x200, v1
	v_cmp_lt_u32_e32 vcc, s3, v1
	global_store_dword v[4:5], v3, off sc1
	s_or_b64 s[4:5], vcc, s[4:5]
	v_lshl_add_u64 v[4:5], v[4:5], 0, s[6:7]
	s_andn2_b64 exec, exec, s[4:5]
	s_cbranch_execnz .LBB0_4
	s_or_b64 exec, exec, s[4:5]
	buffer_wbl2 sc1
	s_waitcnt vmcnt(0)
	buffer_inv sc1
	s_and_saveexec_b64 s[6:7], s[38:39]
	s_load_dwordx2 s[8:9], s[88:89], 0x58
	v_mov_b32_e32 v2, 0
	v_mov_b32_e32 v3, 1
	s_waitcnt lgkmcnt(0)
	global_atomic_add v2, v3, s[8:9] offset:32
	s_waitcnt vmcnt(0)
	s_or_b64 exec, exec, s[6:7]

.LBB0_17:
	s_load_dwordx2 s[4:5], s[0:1], 0xe8
	s_getreg_b32 s3, hwreg(HW_REG_XCC_ID, 0, 4)
	s_and_saveexec_b64 s[6:7], s[38:39]
	s_cbranch_execz .Lgs_done
	s_load_dwordx2 s[8:9], s[88:89], 0x58
	v_mov_b32_e32 v0, 0
	s_mov_b32 s10, 0
	s_waitcnt lgkmcnt(0)
.Lgs_poll:
	global_load_dword v2, v0, s[8:9] offset:32 sc1
	s_waitcnt vmcnt(0)
	v_and_b32_e32 v2, 0xffff, v2
	v_cmp_ne_u32_e32 vcc, 0, v2
	s_cbranch_vccnz .Lgs_seen
	s_sleep 1
	s_add_i32 s10, s10, 1
	s_cmp_lt_u32 s10, 0x8000
	s_cbranch_scc1 .Lgs_poll

.Lgs_done:
	s_or_b64 exec, exec, s[6:7]
	s_waitcnt lgkmcnt(0)
	s_and_saveexec_b64 s[6:7], s[38:39]
	s_cbranch_execz .LBB0_30
	s_mov_b64 s[8:9], exec
	v_mbcnt_lo_u32_b32 v0, s8, 0
	v_mbcnt_hi_u32_b32 v0, s9, v0
	v_cmp_eq_u32_e32 vcc, 0, v0
	s_and_b64 s[10:11], exec, vcc
	s_mov_b64 exec, s[10:11]
	s_cbranch_execz .LBB0_30
	s_lshl_b32 s3, s3, 8
	s_and_b32 s3, s3, 0xf00
	s_add_u32 s4, s4, s3
	s_addc_u32 s5, s5, 0
	s_bcnt1_i32_b64 s3, s[8:9]
	v_mov_b32_e32 v0, 0x7798000
	v_mov_b32_e32 v1, s3
	global_atomic_add v0, v1, s[4:5] offset:1024
.LBB0_30:
	s_or_b64 exec, exec, s[6:7]
	s_mov_b64 s[6:7], s[0:1]
	s_getreg_b32 s3, hwreg(HW_REG_XCC_ID, 0, 4)
	s_waitcnt vmcnt(0)
	s_barrier
	s_and_saveexec_b64 s[4:5], s[38:39]
	s_cbranch_execz .Lxb0_123
	s_add_i32 s8, 0, 0x22000
	v_mov_b32_e32 v0, s8
	s_load_dwordx2 s[6:7], s[6:7], 0xe8
	s_waitcnt vmcnt(0) expcnt(0) lgkmcnt(0)
	ds_read_b32 v2, v0
	s_add_i32 s8, 0, 0x22004
	v_mov_b32_e32 v0, s8
	ds_read_b32 v0, v0
	s_and_b32 s3, s3, 15
	s_waitcnt lgkmcnt(1)
	v_cmp_ne_u32_e32 vcc, 0, v2
	s_cbranch_vccnz .Lxb0_87
	s_load_dword s8, s[88:89], 0x14
	s_mov_b32 s33, 1
	v_mov_b32_e32 v16, 0
	s_waitcnt lgkmcnt(0)
	s_lshr_b32 s10, s8, 16
	s_and_b32 s8, s8, 0xffff
	s_cmp_lg_u32 s8, 0
	s_cselect_b64 s[8:9], -1, 0
	s_cmp_lg_u64 s[8:9], 0
	s_addc_u32 s8, s43, 0
	s_cmp_lg_u32 s10, 0
	s_mul_i32 s58, s8, s42
	s_cselect_b64 s[8:9], -1, 0
	s_cmp_lg_u64 s[8:9], 0
	s_addc_u32 s8, s90, 0
	s_mul_i32 s58, s58, s8
	s_add_u32 s8, s6, 0x7798200
	s_addc_u32 s9, s7, 0
	s_add_u32 s10, s6, 0x7798400
	s_addc_u32 s11, s7, 0
	s_add_u32 s12, s6, 0x7798500
	s_addc_u32 s13, s7, 0
	s_add_u32 s14, s6, 0x7798600
	s_addc_u32 s15, s7, 0
	s_add_u32 s16, s6, 0x7798700
	s_addc_u32 s17, s7, 0
	s_add_u32 s18, s6, 0x7798800
	s_addc_u32 s19, s7, 0
	s_add_u32 s20, s6, 0x7798900
	s_addc_u32 s21, s7, 0
	s_add_u32 s22, s6, 0x7798a00
	s_addc_u32 s23, s7, 0
	s_add_u32 s24, s6, 0x7798b00
	s_addc_u32 s25, s7, 0
	s_add_u32 s26, s6, 0x7798c00
	s_addc_u32 s27, s7, 0
	s_add_u32 s28, s6, 0x7798d00
	s_addc_u32 s29, s7, 0
	s_add_u32 s30, s6, 0x7798e00
	s_addc_u32 s31, s7, 0
	s_add_u32 s34, s6, 0x7798f00
	s_addc_u32 s35, s7, 0
	s_add_u32 s36, s6, 0x7799000
	s_addc_u32 s37, s7, 0
	s_add_u32 s40, s6, 0x7799100
	s_addc_u32 s41, s7, 0
	s_add_u32 s44, s6, 0x7799200
	s_addc_u32 s45, s7, 0
	s_add_u32 s46, s6, 0x7799300
	s_addc_u32 s47, s7, 0
	s_branch .Lxb0_75

.Lxb0_123:
	s_or_b64 exec, exec, s[4:5]
	s_mov_b64 s[4:5], s[0:1]
	v_mov_b32_e32 v2, v170
	s_waitcnt lgkmcnt(0)
	s_barrier
	s_cmp_lg_u32 s2, 0
	s_cbranch_scc1 .Lgs_noreset
	s_and_saveexec_b64 s[6:7], s[38:39]
	s_load_dwordx2 s[8:9], s[88:89], 0x58
	v_mov_b32_e32 v0, 0
	v_mov_b32_e32 v1, -1
	s_waitcnt lgkmcnt(0)
	global_atomic_add v0, v1, s[8:9] offset:32
	s_or_b64 exec, exec, s[6:7]
.Lgs_noreset:
	s_mov_b64 s[4:5], s[0:1]
	v_mov_b32_e32 v0, v170
	s_cmpk_gt_i32 s2, 0x157
	s_cbranch_scc1 .LBB0_71
	s_load_dwordx2 s[6:7], s[4:5], 0xe8
	v_add_u32_e32 v4, 0x200, v0
	v_ashrrev_i32_e32 v11, 6, v4
	v_add_u32_e32 v4, 0x400, v0
	v_ashrrev_i32_e32 v12, 6, v4
	v_add_u32_e32 v4, 0x600, v0
	v_ashrrev_i32_e32 v13, 6, v4
	v_add_u32_e32 v4, 0x800, v0
	s_waitcnt lgkmcnt(0)
	s_add_u32 s8, s6, 0x780000
	v_ashrrev_i32_e32 v14, 6, v4
	v_add_u32_e32 v4, 0xa00, v0
	s_addc_u32 s9, s7, 0
	v_ashrrev_i32_e32 v15, 6, v4
	v_add_u32_e32 v4, 0xc00, v0
	s_add_u32 s3, s6, 0xe3c000
	v_ashrrev_i32_e32 v16, 6, v4
	v_add_u32_e32 v4, 0xe00, v0
	s_addc_u32 s30, s7, 0
	v_ashrrev_i32_e32 v17, 6, v4
	v_bfe_u32 v4, v0, 4, 2
	v_lshlrev_b32_e32 v5, 4, v0
	v_lshlrev_b32_e32 v3, 3, v0
	s_add_u32 s10, s6, 0xdbc000
	v_mul_u32_u24_e32 v4, 0x4100, v4
	v_and_b32_e32 v5, 0xf0, v5
	s_addc_u32 s11, s7, 0
	v_add3_u32 v5, 0, v4, v5
	v_and_b32_e32 v4, 56, v3
	s_add_u32 s12, s6, 0xbbc000
	v_ashrrev_i32_e32 v18, 3, v0
	v_mul_u32_u24_e32 v3, 0x41, v4
	v_ashrrev_i32_e32 v10, 6, v0
	v_lshlrev_b32_e32 v1, 2, v0
	s_addc_u32 s13, s7, 0
	s_movk_i32 s16, 0x104
	v_lshlrev_b32_e32 v20, 2, v18
	v_lshlrev_b32_e32 v3, 2, v3
	v_and_b32_e32 v2, 0xfc, v1
	s_add_u32 s14, s6, 0x7bc000
	v_mul_lo_u32 v6, v10, s16
	v_mul_lo_u32 v7, v11, s16
	v_mul_lo_u32 v8, v12, s16
	v_mul_lo_u32 v9, v13, s16
	v_mul_lo_u32 v26, v14, s16
	v_mul_lo_u32 v27, v15, s16
	v_mul_lo_u32 v28, v16, s16
	v_mul_lo_u32 v29, v17, s16
	v_add3_u32 v19, 0, v20, v3
	v_add3_u32 v20, 0, v3, v20
	s_addc_u32 s15, s7, 0
	v_mov_b32_e32 v1, 0
	s_mov_b32 s17, 0
	v_lshl_add_u32 v21, s2, 9, v0
	s_lshl_b32 s31, s42, 9
	v_lshlrev_b32_e32 v2, 2, v2
	v_add_u32_e32 v22, v5, v6
	v_add_u32_e32 v23, v5, v7
	v_add_u32_e32 v24, v5, v8
	v_add_u32_e32 v25, v5, v9
	v_add_u32_e32 v26, v5, v26
	v_add_u32_e32 v27, v5, v27
	v_add_u32_e32 v28, v5, v28
	v_add_u32_e32 v29, v5, v29
	v_lshlrev_b32_e32 v4, 1, v4
	s_mov_b32 s34, 0x88888889
	s_movk_i32 s35, 0x8800
	s_mov_b32 s36, 0x2aaaaaab
	s_movk_i32 s37, 0x6000
	s_movk_i32 s40, 0x3ff
	v_add_u32_e32 v30, 0x400, v19
	v_add_u32_e32 v31, 0x400, v20
	v_add_u32_e32 v32, 0x4000, v19
	v_add_u32_e32 v33, 0x4200, v20
	v_add_u32_e32 v34, 0x4400, v19
	v_add_u32_e32 v35, 0x4600, v20
	v_add_u32_e32 v36, 0x8200, v19
	v_add_u32_e32 v37, 0x8200, v20
	v_add_u32_e32 v38, 0x8600, v19
	v_add_u32_e32 v39, 0x8600, v20
	v_add_u32_e32 v40, 0xc200, v19
	v_add_u32_e32 v41, 0xc400, v20
	v_add_u32_e32 v42, 0xc600, v19
	v_add_u32_e32 v43, 0xc800, v20
	s_mov_b32 s41, s2
	s_branch .LBB0_34

.LBB0_1010:
	s_or_b64 exec, exec, s[30:31]
	v_readfirstlane_b32 s8, v0
	s_mul_i32 s36, s8, s42
	s_add_i32 s36, s36, s2
	s_cmpk_gt_i32 s36, 0x19ff
	s_mov_b64 s[30:31], -1
	s_cbranch_scc1 .LBB0_1005
	s_cmpk_gt_i32 s36, 0x1ff
	s_cbranch_scc0 .LBB0_1025
	s_load_dwordx2 s[30:31], s[20:21], 0xe8
	s_lshl_b32 s8, s36, 1
	s_and_b32 s56, s36, 31
	s_and_b32 s37, s8, 0x7fffffc0
	s_addk_i32 s37, 0xfc00
	s_lshl_b32 s8, s56, 6
	s_waitcnt lgkmcnt(0)
	s_add_u32 s34, s30, s8
	s_addc_u32 s35, s31, 0
	v_or_b32_e32 v2, s37, v147
	v_lshl_add_u64 v[0:1], s[34:35], 0, v[144:145]
	v_lshl_add_u64 v[16:17], v[0:1], 0, s[10:11]
	v_lshlrev_b32_e32 v18, 9, v2
	v_mov_b32_e32 v12, 0
	v_mov_b32_e32 v13, 0
	v_mov_b32_e32 v14, 0
	v_mov_b32_e32 v15, 0
	v_mov_b32_e32 v4, 0
	v_mov_b32_e32 v5, 0
	v_mov_b32_e32 v6, 0
	v_mov_b32_e32 v7, 0
	v_mov_b32_e32 v8, 0
	v_mov_b32_e32 v9, 0
	v_mov_b32_e32 v10, 0
	v_mov_b32_e32 v11, 0
	v_mov_b32_e32 v0, 0
	v_mov_b32_e32 v1, 0
	v_mov_b32_e32 v2, 0
	v_mov_b32_e32 v3, 0
	s_mov_b32 s57, 0
	s_and_saveexec_b64 s[60:61], s[6:7]
	s_cbranch_execz .Ls5a_u_skip
	v_mov_b32_e32 v19, v145
	v_lshl_add_u64 v[216:217], v[18:19], 2, v[16:17]
	global_load_dwordx4 v[184:187], v[216:217], off
	global_load_dwordx4 v[188:191], v[216:217], off offset:16
	v_lshl_add_u64 v[218:219], v[216:217], 0, s[12:13]
	global_load_dwordx4 v[192:195], v[218:219], off
	global_load_dwordx4 v[196:199], v[218:219], off offset:16
	v_lshl_add_u64 v[218:219], v[216:217], 0, s[14:15]
	global_load_dwordx4 v[200:203], v[218:219], off
	global_load_dwordx4 v[204:207], v[218:219], off offset:16
	v_lshl_add_u64 v[218:219], v[216:217], 0, s[16:17]
	global_load_dwordx4 v[208:211], v[218:219], off
	global_load_dwordx4 v[212:215], v[218:219], off offset:16
.Ls5a_u_skip:
	s_or_b64 exec, exec, s[60:61]
	v_mov_b32_e32 v151, v145
	s_add_u32 s34, s30, 0x76c8000
	v_lshl_add_u64 v[16:17], s[30:31], 0, v[150:151]
	s_addc_u32 s35, s31, 0
	v_lshl_add_u64 v[16:17], v[16:17], 0, s[18:19]
	s_lshl_b32 s8, s56, 13
	v_lshl_add_u64 v[18:19], v[16:17], 0, s[8:9]
	global_load_dwordx4 v[56:59], v[18:19], off
	global_load_dwordx4 v[52:55], v[18:19], off offset:1024
	global_load_dwordx4 v[48:51], v[18:19], off offset:2048
	global_load_dwordx4 v[72:75], v[18:19], off offset:3072
	v_add_co_u32_e32 v18, vcc, s45, v18
	s_or_b32 s8, s56, 32
	s_nop 0
	v_addc_co_u32_e32 v19, vcc, 0, v19, vcc
	global_load_dwordx4 v[84:87], v[18:19], off
	global_load_dwordx4 v[108:111], v[18:19], off offset:1024
	global_load_dwordx4 v[116:119], v[18:19], off offset:2048
	global_load_dwordx4 v[124:127], v[18:19], off offset:3072
	v_lshl_or_b32 v18, s56, 10, v148
	global_load_dwordx2 v[64:65], v18, s[34:35]
	v_lshl_or_b32 v18, s8, 10, v148
	s_lshl_b32 s8, s8, 13
	v_lshl_add_u64 v[16:17], v[16:17], 0, s[8:9]
	global_load_dwordx2 v[60:61], v18, s[34:35]
	global_load_dwordx4 v[44:47], v[16:17], off
	global_load_dwordx4 v[40:43], v[16:17], off offset:1024
	global_load_dwordx4 v[36:39], v[16:17], off offset:2048
	global_load_dwordx4 v[32:35], v[16:17], off offset:3072
	v_add_co_u32_e32 v16, vcc, s45, v16
	v_add_u32_e32 v66, 0x1000, v179
	s_nop 0
	v_addc_co_u32_e32 v17, vcc, 0, v17, vcc
	global_load_dwordx4 v[28:31], v[16:17], off
	global_load_dwordx4 v[24:27], v[16:17], off offset:1024
	global_load_dwordx4 v[20:23], v[16:17], off offset:2048
	s_nop 0
	global_load_dwordx4 v[16:19], v[16:17], off offset:3072
	s_and_saveexec_b64 s[60:61], s[6:7]
	s_waitcnt vmcnt(18)
	v_cvt_pk_bf16_f32 v12, v184, v185
	v_cvt_pk_bf16_f32 v13, v186, v187
	v_cvt_pk_bf16_f32 v14, v188, v189
	v_cvt_pk_bf16_f32 v15, v190, v191
	v_cvt_pk_bf16_f32 v4, v192, v193
	v_cvt_pk_bf16_f32 v5, v194, v195
	v_cvt_pk_bf16_f32 v6, v196, v197
	v_cvt_pk_bf16_f32 v7, v198, v199
	v_cvt_pk_bf16_f32 v8, v200, v201
	v_cvt_pk_bf16_f32 v9, v202, v203
	v_cvt_pk_bf16_f32 v10, v204, v205
	v_cvt_pk_bf16_f32 v11, v206, v207
	v_cvt_pk_bf16_f32 v0, v208, v209
	v_cvt_pk_bf16_f32 v1, v210, v211
	v_cvt_pk_bf16_f32 v2, v212, v213
	v_cvt_pk_bf16_f32 v3, v214, v215
	s_or_b64 exec, exec, s[60:61]
	s_waitcnt lgkmcnt(0)
	v_add_u32_e32 v67, 0x2000, v179
	v_mov_b32_e32 v62, 0
	v_mov_b32_e32 v63, v62
	s_waitcnt vmcnt(17)
	v_mfma_f32_16x16x32_bf16 v[68:71], v[56:59], v[12:15], 0
	s_nop 7
	v_cvt_pk_bf16_f32 v68, v68, v69
	s_waitcnt vmcnt(16)
	v_mfma_f32_16x16x32_bf16 v[76:79], v[52:55], v[12:15], 0
	v_cvt_pk_bf16_f32 v69, v70, v71
	s_waitcnt vmcnt(15)
	v_mfma_f32_16x16x32_bf16 v[80:83], v[48:51], v[12:15], 0
	s_waitcnt vmcnt(14)
	v_mfma_f32_16x16x32_bf16 v[88:91], v[72:75], v[12:15], 0
	s_nop 2
	v_cvt_pk_bf16_f32 v70, v76, v77
	v_cvt_pk_bf16_f32 v71, v78, v79
	s_nop 0
	v_cvt_pk_bf16_f32 v76, v80, v81
	v_mfma_f32_16x16x32_bf16 v[92:95], v[56:59], v[4:7], 0
	v_cvt_pk_bf16_f32 v77, v82, v83
	v_cvt_pk_bf16_f32 v78, v88, v89
	v_cvt_pk_bf16_f32 v79, v90, v91
	v_mfma_f32_16x16x32_bf16 v[96:99], v[52:55], v[4:7], 0
	ds_write2_b64 v179, v[68:69], v[70:71] offset1:4
	ds_write2_b64 v179, v[76:77], v[78:79] offset0:8 offset1:12
	s_nop 1
	v_cvt_pk_bf16_f32 v80, v92, v93
	v_cvt_pk_bf16_f32 v81, v94, v95
	s_waitcnt vmcnt(13)
	v_mfma_f32_16x16x32_bf16 v[120:123], v[84:87], v[12:15], 0
	v_cvt_pk_bf16_f32 v82, v96, v97
	v_cvt_pk_bf16_f32 v83, v98, v99
	s_waitcnt vmcnt(12)
	v_mfma_f32_16x16x32_bf16 v[128:131], v[108:111], v[12:15], 0
	v_mfma_f32_16x16x32_bf16 v[100:103], v[48:51], v[4:7], 0
	s_nop 2
	v_cvt_pk_bf16_f32 v68, v120, v121
	v_cvt_pk_bf16_f32 v69, v122, v123
	s_nop 1
	v_cvt_pk_bf16_f32 v70, v128, v129
	v_mfma_f32_16x16x32_bf16 v[104:107], v[72:75], v[4:7], 0
	v_cvt_pk_bf16_f32 v71, v130, v131
	v_cvt_pk_bf16_f32 v88, v100, v101
	v_cvt_pk_bf16_f32 v89, v102, v103
	s_waitcnt vmcnt(11)
	v_mfma_f32_16x16x32_bf16 v[132:135], v[116:119], v[12:15], 0
	s_waitcnt vmcnt(10)
	v_mfma_f32_16x16x32_bf16 v[136:139], v[124:127], v[12:15], 0
	s_nop 0
	v_cvt_pk_bf16_f32 v90, v104, v105
	v_cvt_pk_bf16_f32 v91, v106, v107
	s_nop 2
	v_cvt_pk_bf16_f32 v76, v132, v133
	v_mfma_f32_16x16x32_bf16 v[140:143], v[84:87], v[4:7], 0
	v_cvt_pk_bf16_f32 v77, v134, v135
	v_cvt_pk_bf16_f32 v78, v136, v137
	v_cvt_pk_bf16_f32 v79, v138, v139
	v_mfma_f32_16x16x32_bf16 v[154:157], v[108:111], v[4:7], 0
	ds_write2_b64 v66, v[80:81], v[82:83] offset0:32 offset1:36
	ds_write2_b64 v66, v[88:89], v[90:91] offset0:40 offset1:44
	s_nop 1
	v_cvt_pk_bf16_f32 v80, v140, v141
	v_cvt_pk_bf16_f32 v81, v142, v143
	v_mfma_f32_16x16x32_bf16 v[158:161], v[116:119], v[4:7], 0
	s_nop 0
	v_cvt_pk_bf16_f32 v82, v154, v155
	v_cvt_pk_bf16_f32 v83, v156, v157
	ds_write2_b64 v179, v[68:69], v[70:71] offset0:16 offset1:20
	ds_write2_b64 v179, v[76:77], v[78:79] offset0:24 offset1:28
	ds_write2_b64 v66, v[80:81], v[82:83] offset0:48 offset1:52
	v_mfma_f32_16x16x32_bf16 v[162:165], v[124:127], v[4:7], 0
	s_nop 0
	v_cvt_pk_bf16_f32 v88, v158, v159
	v_cvt_pk_bf16_f32 v89, v160, v161
	v_mfma_f32_16x16x32_bf16 v[112:115], v[56:59], v[8:11], 0
	v_mfma_f32_16x16x32_bf16 v[68:71], v[52:55], v[8:11], 0
	s_nop 2
	v_cvt_pk_bf16_f32 v76, v162, v163
	v_cvt_pk_bf16_f32 v77, v164, v165
	ds_write2_b64 v66, v[88:89], v[76:77] offset0:56 offset1:60
	v_mfma_f32_16x16x32_bf16 v[76:79], v[48:51], v[8:11], 0
	v_cvt_pk_bf16_f32 v88, v112, v113
	v_cvt_pk_bf16_f32 v89, v114, v115
	v_cvt_pk_bf16_f32 v68, v68, v69
	v_mfma_f32_16x16x32_bf16 v[80:83], v[72:75], v[8:11], 0
	v_cvt_pk_bf16_f32 v69, v70, v71
	ds_write2_b64 v67, v[88:89], v[68:69] offset0:64 offset1:68
	s_nop 1
	v_cvt_pk_bf16_f32 v88, v76, v77
	v_mfma_f32_16x16x32_bf16 v[68:71], v[84:87], v[8:11], 0
	v_cvt_pk_bf16_f32 v89, v78, v79
	s_nop 0
	v_cvt_pk_bf16_f32 v80, v80, v81
	v_cvt_pk_bf16_f32 v81, v82, v83
	v_mfma_f32_16x16x32_bf16 v[76:79], v[108:111], v[8:11], 0
	ds_write2_b64 v67, v[88:89], v[80:81] offset0:72 offset1:76
	s_nop 1
	v_cvt_pk_bf16_f32 v88, v68, v69
	v_cvt_pk_bf16_f32 v89, v70, v71
	v_mfma_f32_16x16x32_bf16 v[80:83], v[116:119], v[8:11], 0
	v_mfma_f32_16x16x32_bf16 v[68:71], v[124:127], v[8:11], 0
	s_nop 0
	v_cvt_pk_bf16_f32 v76, v76, v77
	v_cvt_pk_bf16_f32 v77, v78, v79
	ds_write2_b64 v67, v[88:89], v[76:77] offset0:80 offset1:84
	v_mfma_f32_16x16x32_bf16 v[56:59], v[56:59], v[0:3], 0
	s_nop 1
	v_cvt_pk_bf16_f32 v76, v80, v81
	v_cvt_pk_bf16_f32 v77, v82, v83
	v_cvt_pk_bf16_f32 v68, v68, v69
	v_mfma_f32_16x16x32_bf16 v[52:55], v[52:55], v[0:3], 0
	v_cvt_pk_bf16_f32 v69, v70, v71
	ds_write2_b64 v67, v[76:77], v[68:69] offset0:88 offset1:92
	v_cvt_pk_bf16_f32 v68, v56, v57
	v_mfma_f32_16x16x32_bf16 v[48:51], v[48:51], v[0:3], 0
	v_cvt_pk_bf16_f32 v69, v58, v59
	s_nop 2
	v_cvt_pk_bf16_f32 v52, v52, v53
	v_cvt_pk_bf16_f32 v53, v54, v55
	v_add_u32_e32 v56, 0x3000, v179
	ds_write2_b64 v56, v[68:69], v[52:53] offset0:96 offset1:100
	v_mfma_f32_16x16x32_bf16 v[52:55], v[72:75], v[0:3], 0
	v_cvt_pk_bf16_f32 v58, v48, v49
	v_cvt_pk_bf16_f32 v59, v50, v51
	v_mfma_f32_16x16x32_bf16 v[48:51], v[84:87], v[0:3], 0
	s_nop 4
	v_cvt_pk_bf16_f32 v52, v52, v53
	v_cvt_pk_bf16_f32 v53, v54, v55
	ds_write2_b64 v56, v[58:59], v[52:53] offset0:104 offset1:108
	v_mfma_f32_16x16x32_bf16 v[52:55], v[108:111], v[0:3], 0
	v_cvt_pk_bf16_f32 v58, v48, v49
	v_cvt_pk_bf16_f32 v59, v50, v51
	v_mfma_f32_16x16x32_bf16 v[48:51], v[116:119], v[0:3], 0
	s_nop 4
	v_cvt_pk_bf16_f32 v52, v52, v53
	v_cvt_pk_bf16_f32 v53, v54, v55
	ds_write2_b64 v56, v[58:59], v[52:53] offset0:112 offset1:116
	v_cvt_pk_bf16_f32 v52, v48, v49
	v_cvt_pk_bf16_f32 v53, v50, v51
	v_mfma_f32_16x16x32_bf16 v[48:51], v[124:127], v[0:3], 0
	s_nop 7
	v_cvt_pk_bf16_f32 v48, v48, v49
	v_cvt_pk_bf16_f32 v49, v50, v51
	ds_write2_b64 v56, v[52:53], v[48:49] offset0:120 offset1:124
	s_waitcnt lgkmcnt(0)
	s_waitcnt vmcnt(9)
	v_xor_b32_e32 v49, 0x80000000, v65
	v_mov_b32_e32 v48, v65
	v_mov_b32_e32 v50, v64
	v_mov_b32_e32 v51, v64
	v_mov_b32_e32 v64, v49
	v_pk_mov_b32 v[52:53], v[48:49], v[48:49] op_sel:[1,0]
	v_pk_mov_b32 v[54:55], v[64:65], v[64:65] op_sel:[1,0]
